# split-tail token first for blocks >=256 and last for blocks <256 (de-synchronises the two waves of a SIMD)
# speedup vs baseline: 1.0047x; 1.0047x over previous
.LBB0_324:
	s_nop 0
	v_readlane_b32 s0, v249, 46
	v_readlane_b32 s1, v249, 47
	s_and_b64 vcc, exec, s[0:1]
	s_cbranch_vccz .LBB0_345
	v_mov_b32_e32 v1, v220
	v_readlane_b32 s0, v249, 0
	s_nop 0
	v_ashrrev_i32_e32 v0, 6, v1
	v_lshl_add_u32 v116, s0, 2, v0
	v_readfirstlane_b32 s60, v0
	v_readlane_b32 s55, v249, 9
	s_mov_b32 s54, 0
	s_movk_i32 s56, 0x4200
	s_mov_b32 s58, 0
	s_mov_b32 s59, 0
	s_movk_i32 s61, 0xe00
	s_cmp_eq_u32 s55, 0x800
	s_cselect_b32 s55, 1, 0
	s_cselect_b32 s56, 0x4000, s56
	s_sub_u32 s57, s56, 1
	s_lshl_b32 s62, s60, 13
	s_or_b32 s62, s62, 0x8000
	v_readlane_b32 s63, v249, 0
	s_mov_b32 s45, 0
	s_bitcmp1_b32 s63, 8
	s_cselect_b32 s32, 0, 8
	s_add_u32 s2, s63, 0x4000
	s_lshr_b32 s63, s63, 7
	s_and_b32 s63, s63, 2
	s_cmp_eq_u32 s55, 0
	s_cbranch_scc1 .Lg_entry_main
	s_cmp_lg_u32 s32, 0
	s_cbranch_scc1 .Lg_entry_main
	s_mov_b32 s32, -1
	s_mov_b32 s54, 1
	s_lshl_b32 s58, s60, 8
	s_movk_i32 s61, 0x200
	v_readfirstlane_b32 s47, v116
	v_readlane_b32 s3, v249, 9
	s_sub_u32 s47, s47, s3
	v_mov_b32_e32 v116, s2
